# phase 0: all weight-transpose items in the hand-written pipelined loop (tail items included), uniform distribution
# baseline (speedup 1.0000x reference)
.LBB0_92:
	v_lshl_add_u32 v20, s2, 3, v145
	s_waitcnt lgkmcnt(0)
	s_barrier
	s_cmp_lg_u32 s70, 0x100
	s_cbranch_scc1 .Lp0_skip
	v_readfirstlane_b32 s72, v20
	v_and_b32_e32 v200, 31, v144
	v_lshlrev_b32_e32 v100, 2, v200
	v_lshrrev_b32_e32 v101, 5, v144
	v_lshlrev_b32_e32 v201, 14, v145
	v_mul_u32_u24_e32 v202, 0x84, v101
	v_add3_u32 v102, v201, v202, v100
	v_and_b32_e32 v200, 7, v144
	v_lshrrev_b32_e32 v105, 3, v144
	v_mul_u32_u24_e32 v202, 0x420, v200
	v_lshlrev_b32_e32 v203, 2, v105
	v_add3_u32 v103, v201, v202, v203
	v_lshlrev_b32_e32 v104, 4, v200
	v_mov_b32_e32 v106, 0x80
	s_mov_b32 s73, 0
	s_mov_b32 s98, s72
	v_readfirstlane_b32 s75, v145
	s_cmp_gt_u32 s2, 0x7f
	s_cselect_b32 s63, 1, 0
	s_cmp_gt_u32 s2, 0xbf
	s_cselect_b32 s63, 0, s63
	s_cselect_b32 s95, 64, 0
	s_sub_u32 s99, s2, s95
	s_lshl_b32 s99, s99, 3
	s_add_u32 s99, s99, s75
	s_cmp_lt_u32 s72, 0x800
	s_cbranch_scc1 .Lp0_m0_a
	s_cmp_lt_u32 s72, 0x1800
	s_cbranch_scc1 .Lp0_m1_a
	s_cmp_lt_u32 s72, 0x4400
	s_cbranch_scc1 .Lp0_m2_a
	s_cmp_lt_u32 s72, 0x7000
	s_cbranch_scc1 .Lp0_m3_a
	s_cmp_lt_u32 s72, 0x8600
	s_cbranch_scc1 .Lp0_m4_a
	s_cmp_lt_u32 s72, 0x9c00
	s_cbranch_scc1 .Lp0_m5_a
	s_cmp_lt_u32 s72, 0xb860
	s_cbranch_scc1 .Lp0_m6_a
	s_sub_u32 s74, s72, 0xb860
	s_mov_b64 s[76:77], s[22:23]
	s_add_u32 s78, s30, 0xe800000
	s_addc_u32 s79, s31, 0
	s_movk_i32 s80, 0x800
	s_movk_i32 s81, 0x800
	s_mov_b32 s82, 0
	s_movk_i32 s83, 0x0
	s_lshr_b32 s84, s74, 6
	s_and_b32 s85, s74, 63
	s_branch .Lp0_dd_a

.Lp0_loop:
	ds_write_b32 v102, v150
	ds_write_b32 v102, v151 offset:264
	ds_write_b32 v102, v152 offset:528
	ds_write_b32 v102, v153 offset:792
	ds_write_b32 v102, v154 offset:1056
	ds_write_b32 v102, v155 offset:1320
	ds_write_b32 v102, v156 offset:1584
	ds_write_b32 v102, v157 offset:1848
	ds_write_b32 v102, v158 offset:2112
	ds_write_b32 v102, v159 offset:2376
	ds_write_b32 v102, v160 offset:2640
	ds_write_b32 v102, v161 offset:2904
	ds_write_b32 v102, v162 offset:3168
	ds_write_b32 v102, v163 offset:3432
	ds_write_b32 v102, v164 offset:3696
	ds_write_b32 v102, v165 offset:3960
	ds_write_b32 v102, v166 offset:4224
	ds_write_b32 v102, v167 offset:4488
	ds_write_b32 v102, v168 offset:4752
	ds_write_b32 v102, v169 offset:5016
	ds_write_b32 v102, v170 offset:5280
	ds_write_b32 v102, v171 offset:5544
	ds_write_b32 v102, v172 offset:5808
	ds_write_b32 v102, v173 offset:6072
	ds_write_b32 v102, v174 offset:6336
	ds_write_b32 v102, v175 offset:6600
	ds_write_b32 v102, v176 offset:6864
	ds_write_b32 v102, v177 offset:7128
	ds_write_b32 v102, v178 offset:7392
	ds_write_b32 v102, v179 offset:7656
	ds_write_b32 v102, v180 offset:7920
	ds_write_b32 v102, v181 offset:8184
	s_add_u32 s73, s73, 1
	s_mov_b32 s64, 1
	s_lshl_b32 s72, s73, 11
	s_add_u32 s72, s72, s98
	s_cmp_lt_u32 s73, 24
	s_cbranch_scc1 .Lp0_nx
	s_sub_u32 s75, s73, 24
	s_mul_i32 s75, s75, 0x600
	s_add_u32 s72, s75, s99
	s_add_u32 s72, s72, 0xc000
	s_cmp_lt_u32 s72, 0xc060
	s_cselect_b32 s64, 1, 0
	s_cmp_eq_u32 s63, 1
	s_cselect_b32 s64, 0, s64
.Lp0_nx:
	s_cmp_eq_u32 s64, 0
	s_cbranch_scc1 .Lp0_nold
	s_cmp_lt_u32 s72, 0x800
	s_cbranch_scc1 .Lp0_m0_b
	s_cmp_lt_u32 s72, 0x1800
	s_cbranch_scc1 .Lp0_m1_b
	s_cmp_lt_u32 s72, 0x4400
	s_cbranch_scc1 .Lp0_m2_b
	s_cmp_lt_u32 s72, 0x7000
	s_cbranch_scc1 .Lp0_m3_b
	s_cmp_lt_u32 s72, 0x8600
	s_cbranch_scc1 .Lp0_m4_b
	s_cmp_lt_u32 s72, 0x9c00
	s_cbranch_scc1 .Lp0_m5_b
	s_cmp_lt_u32 s72, 0xb860
	s_cbranch_scc1 .Lp0_m6_b
	s_sub_u32 s74, s72, 0xb860
	s_mov_b64 s[76:77], s[22:23]
	s_add_u32 s78, s30, 0xe800000
	s_addc_u32 s79, s31, 0
	s_movk_i32 s80, 0x800
	s_movk_i32 s81, 0x800
	s_mov_b32 s82, 0
	s_movk_i32 s83, 0x0
	s_lshr_b32 s84, s74, 6
	s_and_b32 s85, s74, 63
	s_branch .Lp0_dd_b

.Lp0_nost3:
	s_cmp_eq_u32 s64, 0
	s_cbranch_scc1 .Lp0_done
	s_mov_b32 s97, s94
	s_lshl_b32 s95, s87, 1
	s_add_u32 s92, s78, s95
	s_addc_u32 s93, s79, 0
	s_mov_b32 s94, s91
	s_lshl_b32 s96, s80, 1
	v_mov_b32_e32 v142, s83
	s_cmp_eq_u32 s82, 0
	s_cbranch_scc1 .Lp0_r0_b
	s_cmp_eq_u32 s82, 1
	s_cbranch_scc1 .Lp0_r1_b
	s_cmp_lt_u32 s86, 0x1000
	s_cbranch_scc1 .Lp0_r3a_b
	s_cmp_lt_u32 s86, 0x1800
	s_cbranch_scc1 .Lp0_r0_b
	s_cmp_lt_u32 s86, 0x1c00
	s_cbranch_scc1 .Lp0_r3c_b
	s_add_u32 s95, s86, 0
	v_add_u32_e32 v143, s95, v105
	v_add_u32_e32 v200, 0xffffe3f0, v143
	v_and_b32_e32 v201, 32, v200
	v_lshlrev_b32_e32 v201, 2, v201
	v_and_b32_e32 v200, 31, v200
	v_add_u32_e32 v200, 0x1c00, v200
	v_add_u32_e32 v200, v200, v201
	v_mov_b32_e32 v202, 0x1c10
	v_cmp_gt_u32_e32 vcc, v202, v143
	v_add_u32_e32 v201, 32, v143
	s_nop 0
	v_cndmask_b32_e32 v203, v200, v201, vcc
	v_mad_u32_u24 v108, v203, s96, v104
	s_add_u32 s95, s86, 8
	v_add_u32_e32 v143, s95, v105
	v_add_u32_e32 v200, 0xffffe3f0, v143
	v_and_b32_e32 v201, 32, v200
	v_lshlrev_b32_e32 v201, 2, v201
	v_and_b32_e32 v200, 31, v200
	v_add_u32_e32 v200, 0x1c00, v200
	v_add_u32_e32 v200, v200, v201
	v_mov_b32_e32 v202, 0x1c10
	v_cmp_gt_u32_e32 vcc, v202, v143
	v_add_u32_e32 v201, 32, v143
	s_nop 0
	v_cndmask_b32_e32 v203, v200, v201, vcc
	v_mad_u32_u24 v109, v203, s96, v104
	s_add_u32 s95, s86, 16
	v_add_u32_e32 v143, s95, v105
	v_add_u32_e32 v200, 0xffffe3f0, v143
	v_and_b32_e32 v201, 32, v200
	v_lshlrev_b32_e32 v201, 2, v201
	v_and_b32_e32 v200, 31, v200
	v_add_u32_e32 v200, 0x1c00, v200
	v_add_u32_e32 v200, v200, v201
	v_mov_b32_e32 v202, 0x1c10
	v_cmp_gt_u32_e32 vcc, v202, v143
	v_add_u32_e32 v201, 32, v143
	s_nop 0
	v_cndmask_b32_e32 v203, v200, v201, vcc
	v_mad_u32_u24 v110, v203, s96, v104
	s_add_u32 s95, s86, 24
	v_add_u32_e32 v143, s95, v105
	v_add_u32_e32 v200, 0xffffe3f0, v143
	v_and_b32_e32 v201, 32, v200
	v_lshlrev_b32_e32 v201, 2, v201
	v_and_b32_e32 v200, 31, v200
	v_add_u32_e32 v200, 0x1c00, v200
	v_add_u32_e32 v200, v200, v201
	v_mov_b32_e32 v202, 0x1c10
	v_cmp_gt_u32_e32 vcc, v202, v143
	v_add_u32_e32 v201, 32, v143
	s_nop 0
	v_cndmask_b32_e32 v203, v200, v201, vcc
	v_mad_u32_u24 v140, v203, s96, v104
	s_branch .Lp0_rd_b

.Lp0_done:
	v_add_u32_e32 v20, 0xc000, v20
	v_mov_b32_e32 v200, 0xc060
	v_cmp_gt_u32_e32 vcc, v200, v20
	v_add_u32_e32 v201, 0x800, v20
	s_nop 0
	v_cndmask_b32_e32 v20, v20, v201, vcc
